# attention: one static s_setprio 1 for waves 4-7 for the whole attention phase, reset at phase exit
# baseline (speedup 1.0000x reference)
; #define LAS __attribute__((address_space(3)))
; #define LOCAL_IDS() int tid = threadIdx.x; asm volatile("" : "+v"(tid)); const int lane = tid & 63, wave = __builtin_amdgcn_readfirstlane(tid >> 6), gw = vcu * NWAVES + wave; (void)lane; (void)gw
; __global__ void __launch_bounds__(NWAVES * 64, 2) mega_fwd(Args args) {
;     ...
;     {
;         LOCAL_IDS();
;         const float sa = wave_sum(lq1[lane] * lk1[lane], lane), sb = wave_sum(lq2[lane] * lk2[lane], lane);
;         const float lam = expf(sa) - expf(sb) + LAMBDA_INIT1;
;         const float* nrm = (const float*)(ws + WS_CTL + 131072);
;         unsigned* qcnt = (unsigned*)(ws + WS_CTL) + 8192;
;         LAS int* uq = (LAS int*)(lds + attn::OFF_UQ);
;         const int myx = (int)(xbar.x & 7u);
;         for (;;) {
;             if (tid == 0) { int unit = -1;
;                 for (int k = 0; k < 8; ++k) { const int y = (myx + k) & 7; const unsigned e = atomicAdd(qcnt + 64 * y, 1u); if (e < 256u) { unit = y * 256 + (int)e; break; } }
.LBB0_875:
	s_or_b64 exec, exec, s[8:9]
	s_waitcnt lgkmcnt(0)
	v_mov_b32_e32 v0, v248
	s_barrier
	v_bfrev_b32_e32 v6, 0.5
	v_lshlrev_b32_e32 v1, 2, v0
	v_and_b32_e32 v2, 0xfc, v1
	global_load_dword v3, v2, s[50:51]
	global_load_dword v4, v2, s[16:17]
	global_load_dword v5, v2, s[18:19]
	s_nop 0
	global_load_dword v2, v2, s[20:21]
	s_movk_i32 s6, 0x80
	v_cmp_eq_u32_e64 s[8:9], 0, v0
	v_bitop3_b32 v0, v1, 4, v6 bitop3:0x6c
	v_bitop3_b32 v8, v1, 8, v6 bitop3:0x6c
	v_bitop3_b32 v9, v1, 16, v6 bitop3:0x6c
	v_bitop3_b32 v10, v1, 32, v6 bitop3:0x6c
	v_bitop3_b32 v11, v1, 64, v6 bitop3:0x6c
	v_bitop3_b32 v1, v1, s6, v6 bitop3:0x6c
	s_add_u32 s5, s54, 0x1c008000
	s_addc_u32 s7, s55, 0
	s_and_b32 s88, s3, 7
	s_lshl_b32 s10, s88, 8
	s_add_u32 s20, s5, s10
	s_addc_u32 s21, s7, 0
	s_add_i32 s6, s3, 1
	s_and_b32 s89, s6, 7
	s_lshl_b32 s6, s89, 8
	s_add_u32 s46, s5, s6
	s_addc_u32 s47, s7, 0
	s_add_i32 s6, s3, 2
	s_and_b32 s90, s6, 7
	s_lshl_b32 s6, s90, 8
	s_add_u32 s48, s5, s6
	s_addc_u32 s49, s7, 0
	s_add_i32 s6, s3, 3
	s_and_b32 s91, s6, 7
	s_lshl_b32 s6, s91, 8
	s_add_u32 s50, s5, s6
	s_addc_u32 s51, s7, 0
	s_xor_b32 s6, s88, 4
	v_writelane_b32 v255, s6, 12
	s_lshl_b32 s6, s6, 8
	s_add_u32 s60, s5, s6
	s_addc_u32 s61, s7, 0
	s_add_i32 s6, s3, 5
	s_mov_b32 s4, 0x3fb8aa3b
	s_and_b32 s6, s6, 7
	v_writelane_b32 v255, s6, 13
	s_lshl_b32 s6, s6, 8
	s_add_u32 s62, s5, s6
	s_addc_u32 s63, s7, 0
	s_add_i32 s6, s3, 6
	s_and_b32 s6, s6, 7
	v_writelane_b32 v255, s6, 14
	s_lshl_b32 s6, s6, 8
	s_add_u32 s10, s5, s6
	s_mov_b32 s0, 0xc2ce8ed0
	s_addc_u32 s11, s7, 0
	v_writelane_b32 v255, s10, 15
	s_add_i32 s3, s3, -1
	s_mov_b32 s1, 0x42b17218
	v_writelane_b32 v255, s11, 16
	s_and_b32 s3, s3, 7
	v_mov_b32_e32 v7, 0x7f800000
	v_writelane_b32 v255, s3, 17
	s_lshl_b32 s3, s3, 8
	s_add_u32 s6, s5, s3
	s_addc_u32 s7, s7, 0
	v_writelane_b32 v255, s6, 18
	s_mov_b32 s19, 0
	v_mov_b32_e32 v177, 0
	s_movk_i32 s82, 0xff
	s_movk_i32 s83, 0x90
	v_mov_b32_e32 v179, 0xc1800000
	v_bfrev_b32_e32 v184, 1
	v_mov_b32_e32 v185, -1.0
	s_mov_b32 s84, 0x41000000
	s_mov_b32 s85, 0xf800000
	v_mov_b32_e32 v186, 0x260
	v_mov_b32_e32 v187, 0x3727c5ac
	s_mov_b32 s86, 0x3f24fd5c
	s_movk_i32 s87, 0x7fff
	v_mov_b32_e32 v249, 0x42800000
	v_writelane_b32 v255, s7, 19
	s_add_i32 s94, 0, 0x1ac40
	v_mov_b32_e32 v250, 0x3c23d70a
	v_mov_b32_e32 v254, 0xf000
	s_waitcnt vmcnt(2)
	v_mul_f32_e32 v6, v3, v4
	ds_bpermute_b32 v6, v0, v6
	s_waitcnt vmcnt(0)
	v_mul_f32_e32 v12, v5, v2
	ds_bpermute_b32 v0, v0, v12
	v_mov_b32_e32 v198, 0x12660
	v_mov_b32_e32 v188, 0x11460
	s_waitcnt lgkmcnt(1)
	v_fmac_f32_e32 v6, v3, v4
	v_mov_b32_e32 v178, 0x12640
	s_waitcnt lgkmcnt(0)
	v_fmac_f32_e32 v0, v5, v2
	ds_bpermute_b32 v2, v8, v6
	ds_bpermute_b32 v3, v8, v0
	v_mov_b32_e32 v194, 0x11440
	v_mov_b32_e32 v195, 0x11400
	v_mov_b32_e32 v196, 0x12620
	s_waitcnt lgkmcnt(1)
	v_add_f32_e32 v2, v6, v2
	s_waitcnt lgkmcnt(0)
	v_add_f32_e32 v0, v0, v3
	ds_bpermute_b32 v3, v9, v2
	ds_bpermute_b32 v4, v9, v0
	v_mov_b32_e32 v197, 0x11420
	v_mov_b32_e32 v199, 0x13800
	v_mov_b32_e32 v200, 0x12600
	s_waitcnt lgkmcnt(1)
	v_add_f32_e32 v2, v2, v3
	s_waitcnt lgkmcnt(0)
	v_add_f32_e32 v0, v0, v4
	ds_bpermute_b32 v3, v10, v2
	ds_bpermute_b32 v4, v10, v0
	s_waitcnt lgkmcnt(1)
	v_add_f32_e32 v2, v2, v3
	s_waitcnt lgkmcnt(0)
	v_add_f32_e32 v0, v0, v4
	ds_bpermute_b32 v3, v11, v2
	ds_bpermute_b32 v4, v11, v0
	s_waitcnt lgkmcnt(1)
	v_add_f32_e32 v2, v2, v3
	s_waitcnt lgkmcnt(0)
	v_add_f32_e32 v0, v0, v4
	ds_bpermute_b32 v3, v1, v2
	ds_bpermute_b32 v1, v1, v0
	s_waitcnt lgkmcnt(1)
	v_add_f32_e32 v2, v2, v3
	s_waitcnt lgkmcnt(0)
	v_add_f32_e32 v0, v0, v1
	v_mul_f32_e32 v1, 0x3fb8aa3b, v2
	v_mul_f32_e32 v3, 0x3fb8aa3b, v0
	v_fma_f32 v4, v2, s4, -v1
	v_rndne_f32_e32 v5, v1
	v_fma_f32 v6, v0, s4, -v3
	v_rndne_f32_e32 v8, v3
	v_fmac_f32_e32 v4, 0x32a5705f, v2
	v_sub_f32_e32 v1, v1, v5
	v_fmac_f32_e32 v6, 0x32a5705f, v0
	v_sub_f32_e32 v3, v3, v8
	v_add_f32_e32 v1, v1, v4
	v_cvt_i32_f32_e32 v5, v5
	v_add_f32_e32 v3, v3, v6
	v_exp_f32_e32 v1, v1
	v_cvt_i32_f32_e32 v8, v8
	v_exp_f32_e32 v3, v3
	v_cmp_ngt_f32_e32 vcc, s0, v2
	v_ldexp_f32 v1, v1, v5
	s_add_i32 s4, 0, 0x1ac10
	v_ldexp_f32 v3, v3, v8
	v_cndmask_b32_e32 v1, 0, v1, vcc
	v_cmp_ngt_f32_e32 vcc, s0, v0
	s_nop 1
	v_cndmask_b32_e32 v3, 0, v3, vcc
	v_cmp_nlt_f32_e32 vcc, s1, v2
	s_nop 1
	v_cndmask_b32_e32 v1, v7, v1, vcc
	v_cmp_nlt_f32_e32 vcc, s1, v0
	s_nop 1
	v_cndmask_b32_e32 v0, v7, v3, vcc
	v_sub_f32_e32 v0, v1, v0
	v_add_f32_e32 v189, 0x3eb60549, v0
	v_readfirstlane_b32 s98, v248
	s_cmp_ge_u32 s98, 0x100
	s_cbranch_scc0 .Lattn_prio_skip
	s_setprio 1
.Lattn_prio_skip:
	s_branch .LBB0_877

; __device__ __forceinline__ unsigned xb_ld(unsigned* p)              { return __hip_atomic_load(p, __ATOMIC_RELAXED, __HIP_MEMORY_SCOPE_AGENT); }
; __device__ __forceinline__ void xcd_barrier_complete(unsigned* bar, unsigned x, unsigned& nloc, unsigned& nx) {
;     const unsigned G = gridDim.x * gridDim.y * gridDim.z;
;     unsigned sum, cnt, mine, sp = 0u;
;     for (;;) {
;         sum = 0u; cnt = 0u; mine = 0u;
; #pragma unroll
;         for (unsigned j = 0; j < 16; ++j) { const unsigned c = xb_ld(&bar[XB_XCNT(j)]); sum += c; cnt += (c > 0u) ? 1u : 0u; mine = (j == x) ? c : mine; }
; __device__ __forceinline__ void xcd_barrier(const XcdBarrier& b) {
;     asm volatile("s_waitcnt vmcnt(0)" ::: "memory");
;     __syncthreads();
;     if (threadIdx.x == 0) {
;         unsigned* bar = b.bar;
;         __builtin_amdgcn_s_waitcnt(0);
;         unsigned nloc = b.st[0], nx = b.st[1];
;         if (nloc == 0u) { xcd_barrier_complete(bar, b.x, nloc, nx); b.st[0] = nloc; b.st[1] = nx; }
.LBB0_984:
	s_setprio 0
	s_waitcnt vmcnt(0)
	s_waitcnt lgkmcnt(0)
	s_barrier
	s_mov_b64 s[8:9], exec
	v_readlane_b32 s0, v255, 4
	v_readlane_b32 s1, v255, 5
	v_readlane_b32 s78, v255, 8
	s_and_b64 s[0:1], s[8:9], s[0:1]
	v_readlane_b32 s79, v255, 9
	s_mov_b64 exec, s[0:1]
	s_cbranch_execz .LBB0_1036
	s_add_i32 s0, 0, 0x23fc0
	v_mov_b32_e32 v0, s0
	s_waitcnt vmcnt(0) expcnt(0) lgkmcnt(0)
	ds_read_b32 v2, v0
	s_add_i32 s0, 0, 0x23fc4
	v_mov_b32_e32 v0, s0
	ds_read_b32 v0, v0
	s_waitcnt lgkmcnt(1)
	v_cmp_ne_u32_e32 vcc, 0, v2
	s_cbranch_vccnz .LBB0_1000
	s_add_u32 s10, s54, 0x1c000200
	s_addc_u32 s11, s55, 0
	s_add_u32 s12, s54, 0x1c000400
	s_addc_u32 s13, s55, 0
	s_add_u32 s16, s54, 0x1c000500
	s_addc_u32 s17, s55, 0
	s_add_u32 s18, s54, 0x1c000600
	s_addc_u32 s19, s55, 0
	s_add_u32 s20, s54, 0x1c000700
	s_addc_u32 s21, s55, 0
	s_add_u32 s22, s54, 0x1c000800
	s_addc_u32 s23, s55, 0
	s_add_u32 s38, s54, 0x1c000900
	s_addc_u32 s39, s55, 0
	s_add_u32 s42, s54, 0x1c000a00
	s_addc_u32 s43, s55, 0
	s_add_u32 s46, s54, 0x1c000b00
	s_addc_u32 s47, s55, 0
	s_add_u32 s48, s54, 0x1c000c00
	s_addc_u32 s49, s55, 0
	s_add_u32 s50, s54, 0x1c000d00
	s_addc_u32 s51, s55, 0
	s_add_u32 s60, s54, 0x1c000e00
	s_addc_u32 s61, s55, 0
	s_add_u32 s62, s54, 0x1c000f00
	s_addc_u32 s63, s55, 0
	s_add_u32 s64, s54, 0x1c001000
	s_addc_u32 s65, s55, 0
	s_add_u32 s66, s54, 0x1c001100
	s_addc_u32 s67, s55, 0
	s_add_u32 s68, s54, 0x1c001200
	v_readlane_b32 s0, v255, 0
	s_addc_u32 s69, s55, 0
	s_mul_i32 s0, s57, s0
	s_add_u32 s70, s54, 0x1c001300
	s_mul_i32 s0, s0, s56
	s_addc_u32 s71, s55, 0
	s_mov_b32 s1, 1
	v_mov_b32_e32 v16, 0
	s_branch .LBB0_988
